# FoX tile tail: per-wave min of running max via DPP butterfly + readlane instead of 5 serialized ds_bpermute
# baseline (speedup 1.0000x reference)
; template <int TYPE>
; __device__ __forceinline__ void attn_item(const Params& p, int layer, int head, int qb, int mode, LAS unsigned char* lds) {
;     ...
;         if (TYPE == 1) {
;             float mm = m_reg;
; #pragma unroll
;             for (int o_ = 16; o_ >= 1; o_ >>= 1) mm = fminf(mm, __shfl_xor(mm, o_));
;             if (lane == 0) xm[(it2 & 1) * 8 + wid] = mm;
;         }
.LBB0_862:
	v_max_f32_e32 v0, v227, v227
	s_nop 1
	v_min_f32_dpp v0, v0, v0 quad_perm:[1,0,3,2] row_mask:0xf bank_mask:0xf
	s_nop 1
	v_min_f32_dpp v0, v0, v0 quad_perm:[2,3,0,1] row_mask:0xf bank_mask:0xf
	s_nop 1
	v_min_f32_dpp v0, v0, v0 row_half_mirror row_mask:0xf bank_mask:0xf
	s_nop 1
	v_min_f32_dpp v0, v0, v0 row_mirror row_mask:0xf bank_mask:0xf
	s_nop 1
	v_readlane_b32 s4, v0, 16
	s_nop 1
	v_min_f32_e32 v0, s4, v0
	s_and_saveexec_b64 s[4:5], s[36:37]
	s_cbranch_execz .LBB0_864
	s_and_b32 s18, s10, 8
	s_lshl_b32 s18, s18, 2
	s_add_i32 s18, s3, s18
	v_mov_b32_e32 v66, s18
	ds_write_b32 v66, v0
